# v91 with the MLP-up epilogue re-emitted: packed squares, in-place, regular schedule (364 vs ~430 instructions per tile)
# baseline (speedup 1.0000x reference)
.LBB0_1200:
	v_lshl_add_u32 v147, s5, 10, v142
	ds_read_b32 v150, v147
	ds_read_b32 v152, v147 offset:64
	ds_read_b32 v154, v147 offset:128
	ds_read_b32 v156, v147 offset:192
	ds_read_b32 v158, v147 offset:512
	ds_read_b32 v160, v147 offset:576
	ds_read_b32 v162, v147 offset:640
	ds_read_b32 v164, v147 offset:704
	v_lshl_or_b32 v145, s6, 9, v143
	s_lshl_b32 s5, s7, 21
	v_add3_u32 v145, s5, v141, v145
	s_andn2_b64 vcc, exec, s[40:41]
	s_mov_b64 s[40:41], -1
	s_waitcnt lgkmcnt(0)
	v_pk_mul_f32 v[114:115], v[114:115], v[150:151] op_sel_hi:[1,0]
	v_pk_mul_f32 v[116:117], v[116:117], v[150:151] op_sel_hi:[1,0]
	v_pk_mul_f32 v[118:119], v[118:119], v[150:151] op_sel_hi:[1,0]
	v_pk_mul_f32 v[120:121], v[120:121], v[150:151] op_sel_hi:[1,0]
	v_pk_mul_f32 v[122:123], v[122:123], v[150:151] op_sel_hi:[1,0]
	v_pk_mul_f32 v[124:125], v[124:125], v[150:151] op_sel_hi:[1,0]
	v_pk_mul_f32 v[126:127], v[126:127], v[150:151] op_sel_hi:[1,0]
	v_pk_mul_f32 v[128:129], v[128:129], v[150:151] op_sel_hi:[1,0]
	v_max_f32_e32 v114, 0, v114
	v_max_f32_e32 v115, 0, v115
	v_max_f32_e32 v116, 0, v116
	v_max_f32_e32 v117, 0, v117
	v_max_f32_e32 v118, 0, v118
	v_max_f32_e32 v119, 0, v119
	v_max_f32_e32 v120, 0, v120
	v_max_f32_e32 v121, 0, v121
	v_max_f32_e32 v122, 0, v122
	v_max_f32_e32 v123, 0, v123
	v_max_f32_e32 v124, 0, v124
	v_max_f32_e32 v125, 0, v125
	v_max_f32_e32 v126, 0, v126
	v_max_f32_e32 v127, 0, v127
	v_max_f32_e32 v128, 0, v128
	v_max_f32_e32 v129, 0, v129
	v_pk_mul_f32 v[114:115], v[114:115], v[114:115]
	v_pk_mul_f32 v[116:117], v[116:117], v[116:117]
	v_pk_mul_f32 v[118:119], v[118:119], v[118:119]
	v_pk_mul_f32 v[120:121], v[120:121], v[120:121]
	v_pk_mul_f32 v[122:123], v[122:123], v[122:123]
	v_pk_mul_f32 v[124:125], v[124:125], v[124:125]
	v_pk_mul_f32 v[126:127], v[126:127], v[126:127]
	v_pk_mul_f32 v[128:129], v[128:129], v[128:129]
	v_or_b32_e32 v183, 0x100, v145
	v_cvt_pk_bf16_f32 v166, v126, v127
	v_cvt_pk_bf16_f32 v167, v128, v129
	v_cvt_pk_bf16_f32 v168, v122, v123
	v_cvt_pk_bf16_f32 v169, v124, v125
	global_store_dwordx4 v145, v[166:169], s[42:43]
	v_cvt_pk_bf16_f32 v170, v118, v119
	v_cvt_pk_bf16_f32 v171, v120, v121
	v_cvt_pk_bf16_f32 v172, v114, v115
	v_cvt_pk_bf16_f32 v173, v116, v117
	global_store_dwordx4 v183, v[170:173], s[42:43]
	v_pk_mul_f32 v[98:99], v[98:99], v[152:153] op_sel_hi:[1,0]
	v_pk_mul_f32 v[100:101], v[100:101], v[152:153] op_sel_hi:[1,0]
	v_pk_mul_f32 v[102:103], v[102:103], v[152:153] op_sel_hi:[1,0]
	v_pk_mul_f32 v[104:105], v[104:105], v[152:153] op_sel_hi:[1,0]
	v_pk_mul_f32 v[106:107], v[106:107], v[152:153] op_sel_hi:[1,0]
	v_pk_mul_f32 v[108:109], v[108:109], v[152:153] op_sel_hi:[1,0]
	v_pk_mul_f32 v[110:111], v[110:111], v[152:153] op_sel_hi:[1,0]
	v_pk_mul_f32 v[112:113], v[112:113], v[152:153] op_sel_hi:[1,0]
	v_max_f32_e32 v98, 0, v98
	v_max_f32_e32 v99, 0, v99
	v_max_f32_e32 v100, 0, v100
	v_max_f32_e32 v101, 0, v101
	v_max_f32_e32 v102, 0, v102
	v_max_f32_e32 v103, 0, v103
	v_max_f32_e32 v104, 0, v104
	v_max_f32_e32 v105, 0, v105
	v_max_f32_e32 v106, 0, v106
	v_max_f32_e32 v107, 0, v107
	v_max_f32_e32 v108, 0, v108
	v_max_f32_e32 v109, 0, v109
	v_max_f32_e32 v110, 0, v110
	v_max_f32_e32 v111, 0, v111
	v_max_f32_e32 v112, 0, v112
	v_max_f32_e32 v113, 0, v113
	v_pk_mul_f32 v[98:99], v[98:99], v[98:99]
	v_pk_mul_f32 v[100:101], v[100:101], v[100:101]
	v_pk_mul_f32 v[102:103], v[102:103], v[102:103]
	v_pk_mul_f32 v[104:105], v[104:105], v[104:105]
	v_pk_mul_f32 v[106:107], v[106:107], v[106:107]
	v_pk_mul_f32 v[108:109], v[108:109], v[108:109]
	v_pk_mul_f32 v[110:111], v[110:111], v[110:111]
	v_pk_mul_f32 v[112:113], v[112:113], v[112:113]
	v_add_u32_e32 v184, 0x20000, v145
	v_add_u32_e32 v185, 0x20100, v145
	v_cvt_pk_bf16_f32 v174, v110, v111
	v_cvt_pk_bf16_f32 v175, v112, v113
	v_cvt_pk_bf16_f32 v176, v106, v107
	v_cvt_pk_bf16_f32 v177, v108, v109
	global_store_dwordx4 v184, v[174:177], s[42:43]
	v_cvt_pk_bf16_f32 v178, v102, v103
	v_cvt_pk_bf16_f32 v179, v104, v105
	v_cvt_pk_bf16_f32 v180, v98, v99
	v_cvt_pk_bf16_f32 v181, v100, v101
	global_store_dwordx4 v185, v[178:181], s[42:43]
	v_pk_mul_f32 v[82:83], v[82:83], v[154:155] op_sel_hi:[1,0]
	v_pk_mul_f32 v[84:85], v[84:85], v[154:155] op_sel_hi:[1,0]
	v_pk_mul_f32 v[86:87], v[86:87], v[154:155] op_sel_hi:[1,0]
	v_pk_mul_f32 v[88:89], v[88:89], v[154:155] op_sel_hi:[1,0]
	v_pk_mul_f32 v[90:91], v[90:91], v[154:155] op_sel_hi:[1,0]
	v_pk_mul_f32 v[92:93], v[92:93], v[154:155] op_sel_hi:[1,0]
	v_pk_mul_f32 v[94:95], v[94:95], v[154:155] op_sel_hi:[1,0]
	v_pk_mul_f32 v[96:97], v[96:97], v[154:155] op_sel_hi:[1,0]
	v_max_f32_e32 v82, 0, v82
	v_max_f32_e32 v83, 0, v83
	v_max_f32_e32 v84, 0, v84
	v_max_f32_e32 v85, 0, v85
	v_max_f32_e32 v86, 0, v86
	v_max_f32_e32 v87, 0, v87
	v_max_f32_e32 v88, 0, v88
	v_max_f32_e32 v89, 0, v89
	v_max_f32_e32 v90, 0, v90
	v_max_f32_e32 v91, 0, v91
	v_max_f32_e32 v92, 0, v92
	v_max_f32_e32 v93, 0, v93
	v_max_f32_e32 v94, 0, v94
	v_max_f32_e32 v95, 0, v95
	v_max_f32_e32 v96, 0, v96
	v_max_f32_e32 v97, 0, v97
	v_pk_mul_f32 v[82:83], v[82:83], v[82:83]
	v_pk_mul_f32 v[84:85], v[84:85], v[84:85]
	v_pk_mul_f32 v[86:87], v[86:87], v[86:87]
	v_pk_mul_f32 v[88:89], v[88:89], v[88:89]
	v_pk_mul_f32 v[90:91], v[90:91], v[90:91]
	v_pk_mul_f32 v[92:93], v[92:93], v[92:93]
	v_pk_mul_f32 v[94:95], v[94:95], v[94:95]
	v_pk_mul_f32 v[96:97], v[96:97], v[96:97]
	v_add_u32_e32 v182, 0x40000, v145
	v_add_u32_e32 v183, 0x40100, v145
	v_cvt_pk_bf16_f32 v166, v94, v95
	v_cvt_pk_bf16_f32 v167, v96, v97
	v_cvt_pk_bf16_f32 v168, v90, v91
	v_cvt_pk_bf16_f32 v169, v92, v93
	global_store_dwordx4 v182, v[166:169], s[42:43]
	v_cvt_pk_bf16_f32 v170, v86, v87
	v_cvt_pk_bf16_f32 v171, v88, v89
	v_cvt_pk_bf16_f32 v172, v82, v83
	v_cvt_pk_bf16_f32 v173, v84, v85
	global_store_dwordx4 v183, v[170:173], s[42:43]
	v_pk_mul_f32 v[66:67], v[66:67], v[156:157] op_sel_hi:[1,0]
	v_pk_mul_f32 v[68:69], v[68:69], v[156:157] op_sel_hi:[1,0]
	v_pk_mul_f32 v[70:71], v[70:71], v[156:157] op_sel_hi:[1,0]
	v_pk_mul_f32 v[72:73], v[72:73], v[156:157] op_sel_hi:[1,0]
	v_pk_mul_f32 v[74:75], v[74:75], v[156:157] op_sel_hi:[1,0]
	v_pk_mul_f32 v[76:77], v[76:77], v[156:157] op_sel_hi:[1,0]
	v_pk_mul_f32 v[78:79], v[78:79], v[156:157] op_sel_hi:[1,0]
	v_pk_mul_f32 v[80:81], v[80:81], v[156:157] op_sel_hi:[1,0]
	v_max_f32_e32 v66, 0, v66
	v_max_f32_e32 v67, 0, v67
	v_max_f32_e32 v68, 0, v68
	v_max_f32_e32 v69, 0, v69
	v_max_f32_e32 v70, 0, v70
	v_max_f32_e32 v71, 0, v71
	v_max_f32_e32 v72, 0, v72
	v_max_f32_e32 v73, 0, v73
	v_max_f32_e32 v74, 0, v74
	v_max_f32_e32 v75, 0, v75
	v_max_f32_e32 v76, 0, v76
	v_max_f32_e32 v77, 0, v77
	v_max_f32_e32 v78, 0, v78
	v_max_f32_e32 v79, 0, v79
	v_max_f32_e32 v80, 0, v80
	v_max_f32_e32 v81, 0, v81
	v_pk_mul_f32 v[66:67], v[66:67], v[66:67]
	v_pk_mul_f32 v[68:69], v[68:69], v[68:69]
	v_pk_mul_f32 v[70:71], v[70:71], v[70:71]
	v_pk_mul_f32 v[72:73], v[72:73], v[72:73]
	v_pk_mul_f32 v[74:75], v[74:75], v[74:75]
	v_pk_mul_f32 v[76:77], v[76:77], v[76:77]
	v_pk_mul_f32 v[78:79], v[78:79], v[78:79]
	v_pk_mul_f32 v[80:81], v[80:81], v[80:81]
	v_add_u32_e32 v184, 0x60000, v145
	v_add_u32_e32 v185, 0x60100, v145
	v_cvt_pk_bf16_f32 v174, v78, v79
	v_cvt_pk_bf16_f32 v175, v80, v81
	v_cvt_pk_bf16_f32 v176, v74, v75
	v_cvt_pk_bf16_f32 v177, v76, v77
	global_store_dwordx4 v184, v[174:177], s[42:43]
	v_cvt_pk_bf16_f32 v178, v70, v71
	v_cvt_pk_bf16_f32 v179, v72, v73
	v_cvt_pk_bf16_f32 v180, v66, v67
	v_cvt_pk_bf16_f32 v181, v68, v69
	global_store_dwordx4 v185, v[178:181], s[42:43]
	v_pk_mul_f32 v[50:51], v[50:51], v[158:159] op_sel_hi:[1,0]
	v_pk_mul_f32 v[52:53], v[52:53], v[158:159] op_sel_hi:[1,0]
	v_pk_mul_f32 v[54:55], v[54:55], v[158:159] op_sel_hi:[1,0]
	v_pk_mul_f32 v[56:57], v[56:57], v[158:159] op_sel_hi:[1,0]
	v_pk_mul_f32 v[58:59], v[58:59], v[158:159] op_sel_hi:[1,0]
	v_pk_mul_f32 v[60:61], v[60:61], v[158:159] op_sel_hi:[1,0]
	v_pk_mul_f32 v[62:63], v[62:63], v[158:159] op_sel_hi:[1,0]
	v_pk_mul_f32 v[64:65], v[64:65], v[158:159] op_sel_hi:[1,0]
	v_max_f32_e32 v50, 0, v50
	v_max_f32_e32 v51, 0, v51
	v_max_f32_e32 v52, 0, v52
	v_max_f32_e32 v53, 0, v53
	v_max_f32_e32 v54, 0, v54
	v_max_f32_e32 v55, 0, v55
	v_max_f32_e32 v56, 0, v56
	v_max_f32_e32 v57, 0, v57
	v_max_f32_e32 v58, 0, v58
	v_max_f32_e32 v59, 0, v59
	v_max_f32_e32 v60, 0, v60
	v_max_f32_e32 v61, 0, v61
	v_max_f32_e32 v62, 0, v62
	v_max_f32_e32 v63, 0, v63
	v_max_f32_e32 v64, 0, v64
	v_max_f32_e32 v65, 0, v65
	v_pk_mul_f32 v[50:51], v[50:51], v[50:51]
	v_pk_mul_f32 v[52:53], v[52:53], v[52:53]
	v_pk_mul_f32 v[54:55], v[54:55], v[54:55]
	v_pk_mul_f32 v[56:57], v[56:57], v[56:57]
	v_pk_mul_f32 v[58:59], v[58:59], v[58:59]
	v_pk_mul_f32 v[60:61], v[60:61], v[60:61]
	v_pk_mul_f32 v[62:63], v[62:63], v[62:63]
	v_pk_mul_f32 v[64:65], v[64:65], v[64:65]
	v_add_u32_e32 v182, 0x100000, v145
	v_add_u32_e32 v183, 0x100100, v145
	v_cvt_pk_bf16_f32 v166, v62, v63
	v_cvt_pk_bf16_f32 v167, v64, v65
	v_cvt_pk_bf16_f32 v168, v58, v59
	v_cvt_pk_bf16_f32 v169, v60, v61
	global_store_dwordx4 v182, v[166:169], s[42:43]
	v_cvt_pk_bf16_f32 v170, v54, v55
	v_cvt_pk_bf16_f32 v171, v56, v57
	v_cvt_pk_bf16_f32 v172, v50, v51
	v_cvt_pk_bf16_f32 v173, v52, v53
	global_store_dwordx4 v183, v[170:173], s[42:43]
	v_pk_mul_f32 v[34:35], v[34:35], v[160:161] op_sel_hi:[1,0]
	v_pk_mul_f32 v[36:37], v[36:37], v[160:161] op_sel_hi:[1,0]
	v_pk_mul_f32 v[38:39], v[38:39], v[160:161] op_sel_hi:[1,0]
	v_pk_mul_f32 v[40:41], v[40:41], v[160:161] op_sel_hi:[1,0]
	v_pk_mul_f32 v[42:43], v[42:43], v[160:161] op_sel_hi:[1,0]
	v_pk_mul_f32 v[44:45], v[44:45], v[160:161] op_sel_hi:[1,0]
	v_pk_mul_f32 v[46:47], v[46:47], v[160:161] op_sel_hi:[1,0]
	v_pk_mul_f32 v[48:49], v[48:49], v[160:161] op_sel_hi:[1,0]
	v_max_f32_e32 v34, 0, v34
	v_max_f32_e32 v35, 0, v35
	v_max_f32_e32 v36, 0, v36
	v_max_f32_e32 v37, 0, v37
	v_max_f32_e32 v38, 0, v38
	v_max_f32_e32 v39, 0, v39
	v_max_f32_e32 v40, 0, v40
	v_max_f32_e32 v41, 0, v41
	v_max_f32_e32 v42, 0, v42
	v_max_f32_e32 v43, 0, v43
	v_max_f32_e32 v44, 0, v44
	v_max_f32_e32 v45, 0, v45
	v_max_f32_e32 v46, 0, v46
	v_max_f32_e32 v47, 0, v47
	v_max_f32_e32 v48, 0, v48
	v_max_f32_e32 v49, 0, v49
	v_pk_mul_f32 v[34:35], v[34:35], v[34:35]
	v_pk_mul_f32 v[36:37], v[36:37], v[36:37]
	v_pk_mul_f32 v[38:39], v[38:39], v[38:39]
	v_pk_mul_f32 v[40:41], v[40:41], v[40:41]
	v_pk_mul_f32 v[42:43], v[42:43], v[42:43]
	v_pk_mul_f32 v[44:45], v[44:45], v[44:45]
	v_pk_mul_f32 v[46:47], v[46:47], v[46:47]
	v_pk_mul_f32 v[48:49], v[48:49], v[48:49]
	v_add_u32_e32 v184, 0x120000, v145
	v_add_u32_e32 v185, 0x120100, v145
	v_cvt_pk_bf16_f32 v174, v46, v47
	v_cvt_pk_bf16_f32 v175, v48, v49
	v_cvt_pk_bf16_f32 v176, v42, v43
	v_cvt_pk_bf16_f32 v177, v44, v45
	global_store_dwordx4 v184, v[174:177], s[42:43]
	v_cvt_pk_bf16_f32 v178, v38, v39
	v_cvt_pk_bf16_f32 v179, v40, v41
	v_cvt_pk_bf16_f32 v180, v34, v35
	v_cvt_pk_bf16_f32 v181, v36, v37
	global_store_dwordx4 v185, v[178:181], s[42:43]
	v_pk_mul_f32 v[16:17], v[16:17], v[162:163] op_sel_hi:[1,0]
	v_pk_mul_f32 v[18:19], v[18:19], v[162:163] op_sel_hi:[1,0]
	v_pk_mul_f32 v[20:21], v[20:21], v[162:163] op_sel_hi:[1,0]
	v_pk_mul_f32 v[22:23], v[22:23], v[162:163] op_sel_hi:[1,0]
	v_pk_mul_f32 v[24:25], v[24:25], v[162:163] op_sel_hi:[1,0]
	v_pk_mul_f32 v[26:27], v[26:27], v[162:163] op_sel_hi:[1,0]
	v_pk_mul_f32 v[28:29], v[28:29], v[162:163] op_sel_hi:[1,0]
	v_pk_mul_f32 v[30:31], v[30:31], v[162:163] op_sel_hi:[1,0]
	v_max_f32_e32 v16, 0, v16
	v_max_f32_e32 v17, 0, v17
	v_max_f32_e32 v18, 0, v18
	v_max_f32_e32 v19, 0, v19
	v_max_f32_e32 v20, 0, v20
	v_max_f32_e32 v21, 0, v21
	v_max_f32_e32 v22, 0, v22
	v_max_f32_e32 v23, 0, v23
	v_max_f32_e32 v24, 0, v24
	v_max_f32_e32 v25, 0, v25
	v_max_f32_e32 v26, 0, v26
	v_max_f32_e32 v27, 0, v27
	v_max_f32_e32 v28, 0, v28
	v_max_f32_e32 v29, 0, v29
	v_max_f32_e32 v30, 0, v30
	v_max_f32_e32 v31, 0, v31
	v_pk_mul_f32 v[16:17], v[16:17], v[16:17]
	v_pk_mul_f32 v[18:19], v[18:19], v[18:19]
	v_pk_mul_f32 v[20:21], v[20:21], v[20:21]
	v_pk_mul_f32 v[22:23], v[22:23], v[22:23]
	v_pk_mul_f32 v[24:25], v[24:25], v[24:25]
	v_pk_mul_f32 v[26:27], v[26:27], v[26:27]
	v_pk_mul_f32 v[28:29], v[28:29], v[28:29]
	v_pk_mul_f32 v[30:31], v[30:31], v[30:31]
	v_add_u32_e32 v182, 0x140000, v145
	v_add_u32_e32 v183, 0x140100, v145
	v_cvt_pk_bf16_f32 v166, v28, v29
	v_cvt_pk_bf16_f32 v167, v30, v31
	v_cvt_pk_bf16_f32 v168, v24, v25
	v_cvt_pk_bf16_f32 v169, v26, v27
	global_store_dwordx4 v182, v[166:169], s[42:43]
	v_cvt_pk_bf16_f32 v170, v20, v21
	v_cvt_pk_bf16_f32 v171, v22, v23
	v_cvt_pk_bf16_f32 v172, v16, v17
	v_cvt_pk_bf16_f32 v173, v18, v19
	global_store_dwordx4 v183, v[170:173], s[42:43]
	v_pk_mul_f32 v[0:1], v[0:1], v[164:165] op_sel_hi:[1,0]
	v_pk_mul_f32 v[2:3], v[2:3], v[164:165] op_sel_hi:[1,0]
	v_pk_mul_f32 v[4:5], v[4:5], v[164:165] op_sel_hi:[1,0]
	v_pk_mul_f32 v[6:7], v[6:7], v[164:165] op_sel_hi:[1,0]
	v_pk_mul_f32 v[8:9], v[8:9], v[164:165] op_sel_hi:[1,0]
	v_pk_mul_f32 v[10:11], v[10:11], v[164:165] op_sel_hi:[1,0]
	v_pk_mul_f32 v[12:13], v[12:13], v[164:165] op_sel_hi:[1,0]
	v_pk_mul_f32 v[14:15], v[14:15], v[164:165] op_sel_hi:[1,0]
	v_max_f32_e32 v0, 0, v0
	v_max_f32_e32 v1, 0, v1
	v_max_f32_e32 v2, 0, v2
	v_max_f32_e32 v3, 0, v3
	v_max_f32_e32 v4, 0, v4
	v_max_f32_e32 v5, 0, v5
	v_max_f32_e32 v6, 0, v6
	v_max_f32_e32 v7, 0, v7
	v_max_f32_e32 v8, 0, v8
	v_max_f32_e32 v9, 0, v9
	v_max_f32_e32 v10, 0, v10
	v_max_f32_e32 v11, 0, v11
	v_max_f32_e32 v12, 0, v12
	v_max_f32_e32 v13, 0, v13
	v_max_f32_e32 v14, 0, v14
	v_max_f32_e32 v15, 0, v15
	v_pk_mul_f32 v[0:1], v[0:1], v[0:1]
	v_pk_mul_f32 v[2:3], v[2:3], v[2:3]
	v_pk_mul_f32 v[4:5], v[4:5], v[4:5]
	v_pk_mul_f32 v[6:7], v[6:7], v[6:7]
	v_pk_mul_f32 v[8:9], v[8:9], v[8:9]
	v_pk_mul_f32 v[10:11], v[10:11], v[10:11]
	v_pk_mul_f32 v[12:13], v[12:13], v[12:13]
	v_pk_mul_f32 v[14:15], v[14:15], v[14:15]
	v_add_u32_e32 v184, 0x160000, v145
	v_add_u32_e32 v185, 0x160100, v145
	v_cvt_pk_bf16_f32 v174, v12, v13
	v_cvt_pk_bf16_f32 v175, v14, v15
	v_cvt_pk_bf16_f32 v176, v8, v9
	v_cvt_pk_bf16_f32 v177, v10, v11
	global_store_dwordx4 v184, v[174:177], s[42:43]
	v_cvt_pk_bf16_f32 v178, v4, v5
	v_cvt_pk_bf16_f32 v179, v6, v7
	v_cvt_pk_bf16_f32 v180, v0, v1
	v_cvt_pk_bf16_f32 v181, v2, v3
	global_store_dwordx4 v185, v[178:181], s[42:43]
	s_cbranch_vccnz .LBB0_1189
	s_andn2_b64 vcc, exec, s[0:1]
	s_cbranch_vccnz .LBB0_1188
	s_barrier
	s_branch .LBB0_1188
